# v32 plus one static priority raise for waves 4-7 during the indexer phase
# speedup vs baseline: 1.0026x; 1.0026x over previous
.LBB0_394:
	s_or_b64 exec, exec, s[0:1]
	v_mov_b32_e32 v0, v198
	s_waitcnt lgkmcnt(0)
	s_barrier
	s_cselect_b32 s100, 1, 0
	v_writelane_b32 v255, s100, 63
	v_readfirstlane_b32 s100, v198
	s_nop 1
	s_lshr_b32 s100, s100, 6
	s_cmp_lt_u32 s100, 4
	s_cbranch_scc1 .Lprio_idx
	s_setprio 1
.Lprio_idx:
	v_readlane_b32 s100, v255, 63
	s_nop 1
	s_cmp_lg_u32 s100, 0
	s_movk_i32 s0, 0x800
	v_ashrrev_i32_e32 v2, 6, v0
	v_add_u32_e32 v92, s77, v2
	v_cmp_gt_i32_e32 vcc, s0, v92
	s_mov_b64 s[0:1], exec
	v_writelane_b32 v254, s0, 33
	s_nop 1
	v_writelane_b32 v254, s1, 34
	s_and_b64 s[0:1], s[0:1], vcc
	s_mov_b64 exec, s[0:1]
	s_cbranch_execz .LBB0_656
	v_and_b32_e32 v3, 63, v0
	v_and_b32_e32 v93, 31, v0
	v_bfe_u32 v94, v0, 5, 1
	v_bfe_u32 v95, v0, 2, 1
	v_lshrrev_b32_e32 v2, 1, v0
	v_and_b32_e32 v0, 3, v0
	v_and_or_b32 v0, v2, 12, v0
	v_readlane_b32 s0, v251, 3
	v_lshlrev_b32_e32 v2, 6, v0
	v_lshlrev_b32_e32 v0, 6, v94
	v_readlane_b32 s1, v251, 4
	v_lshlrev_b32_e32 v4, 3, v94
	v_or_b32_e32 v96, 32, v93
	v_lshl_add_u64 v[82:83], s[0:1], 0, v[0:1]
	v_readlane_b32 s0, v254, 16
	v_lshlrev_b32_e32 v0, 2, v3
	v_readlane_b32 s1, v254, 17
	v_or_b32_e32 v97, 64, v93
	v_or_b32_e32 v98, 0x60, v93
	v_lshl_add_u64 v[84:85], s[0:1], 0, v[0:1]
	v_cmp_eq_u32_e64 s[0:1], 0, v3
	v_or_b32_e32 v99, 0x80, v93
	v_or_b32_e32 v100, 0xa0, v93
	v_writelane_b32 v254, s0, 35
	v_or_b32_e32 v101, 0xc0, v93
	v_or_b32_e32 v102, 0xe0, v93
	v_writelane_b32 v254, s1, 36
	v_cmp_eq_u32_e64 s[0:1], 1, v3
	v_or_b32_e32 v103, 0x100, v93
	v_or_b32_e32 v104, 0x120, v93
	v_writelane_b32 v254, s0, 37
	v_or_b32_e32 v105, 0x140, v93
	v_or_b32_e32 v106, 0x160, v93
	v_writelane_b32 v254, s1, 38
	v_cmp_eq_u32_e64 s[0:1], 2, v3
	v_or_b32_e32 v107, 0x180, v93
	v_or_b32_e32 v108, 0x1a0, v93
	v_writelane_b32 v254, s0, 39
	v_or_b32_e32 v109, 0x1c0, v93
	v_or_b32_e32 v110, 0x1e0, v93
	v_writelane_b32 v254, s1, 40
	v_cmp_eq_u32_e64 s[0:1], 3, v3
	v_or_b32_e32 v111, 0x200, v93
	v_or_b32_e32 v112, 0x220, v93
	v_writelane_b32 v254, s0, 41
	v_or_b32_e32 v113, 0x240, v93
	v_or_b32_e32 v114, 0x260, v93
	v_writelane_b32 v254, s1, 42
	v_cmp_eq_u32_e64 s[0:1], 4, v3
	v_or_b32_e32 v115, 0x280, v93
	v_or_b32_e32 v116, 0x2a0, v93
	v_writelane_b32 v254, s0, 43
	v_or_b32_e32 v117, 0x2c0, v93
	v_or_b32_e32 v118, 0x2e0, v93
	v_writelane_b32 v254, s1, 44
	v_cmp_eq_u32_e64 s[0:1], 5, v3
	v_or_b32_e32 v119, 0x300, v93
	v_or_b32_e32 v120, 0x320, v93
	v_writelane_b32 v254, s0, 45
	v_or_b32_e32 v121, 0x340, v93
	v_or_b32_e32 v122, 0x360, v93
	v_writelane_b32 v254, s1, 46
	v_cmp_eq_u32_e64 s[0:1], 6, v3
	v_or_b32_e32 v123, 0x380, v93
	v_or_b32_e32 v124, 0x3a0, v93
	v_writelane_b32 v254, s0, 47
	v_or_b32_e32 v125, 0x3c0, v93
	v_or_b32_e32 v126, 0x3e0, v93
	v_writelane_b32 v254, s1, 48
	v_cmp_eq_u32_e64 s[0:1], 7, v3
	v_or_b32_e32 v127, 0x400, v93
	v_or_b32_e32 v128, 0x420, v93
	v_writelane_b32 v254, s0, 49
	v_or_b32_e32 v129, 0x440, v93
	v_or_b32_e32 v130, 0x460, v93
	v_writelane_b32 v254, s1, 50
	v_cmp_eq_u32_e64 s[0:1], 8, v3
	v_or_b32_e32 v131, 0x480, v93
	v_or_b32_e32 v132, 0x4a0, v93
	v_writelane_b32 v254, s0, 51
	v_or_b32_e32 v133, 0x4c0, v93
	v_or_b32_e32 v134, 0x4e0, v93
	v_writelane_b32 v254, s1, 52
	v_cmp_eq_u32_e64 s[0:1], 9, v3
	v_or_b32_e32 v135, 0x500, v93
	v_or_b32_e32 v136, 0x520, v93
	v_writelane_b32 v254, s0, 53
	v_or_b32_e32 v137, 0x540, v93
	v_or_b32_e32 v138, 0x560, v93
	v_writelane_b32 v254, s1, 54
	v_cmp_eq_u32_e64 s[0:1], 10, v3
	v_or_b32_e32 v139, 0x580, v93
	v_or_b32_e32 v140, 0x5a0, v93
	v_writelane_b32 v254, s0, 55
	v_or_b32_e32 v141, 0x5c0, v93
	v_or_b32_e32 v142, 0x5e0, v93
	v_writelane_b32 v254, s1, 56
	v_cmp_eq_u32_e64 s[0:1], 11, v3
	v_or_b32_e32 v143, 0x600, v93
	v_or_b32_e32 v144, 0x620, v93
	v_writelane_b32 v254, s0, 57
	v_or_b32_e32 v145, 0x640, v93
	v_or_b32_e32 v146, 0x660, v93
	v_writelane_b32 v254, s1, 58
	v_cmp_eq_u32_e64 s[0:1], 12, v3
	v_or_b32_e32 v147, 0x680, v93
	v_or_b32_e32 v148, 0x6a0, v93
	v_writelane_b32 v254, s0, 59
	v_or_b32_e32 v149, 0x6c0, v93
	v_or_b32_e32 v150, 0x6e0, v93
	v_writelane_b32 v254, s1, 60
	v_cmp_eq_u32_e64 s[0:1], 13, v3
	v_or_b32_e32 v151, 0x700, v93
	v_or_b32_e32 v152, 0x720, v93
	v_writelane_b32 v254, s0, 61
	v_or_b32_e32 v153, 0x740, v93
	v_or_b32_e32 v154, 0x760, v93
	v_writelane_b32 v254, s1, 62
	v_cmp_eq_u32_e64 s[0:1], 14, v3
	v_or_b32_e32 v155, 0x780, v93
	v_or_b32_e32 v156, 0x7a0, v93
	v_writelane_b32 v254, s0, 63
	v_or_b32_e32 v157, 0x7c0, v93
	v_or_b32_e32 v158, 0x7e0, v93
	v_writelane_b32 v255, s1, 0
	v_cmp_eq_u32_e64 s[0:1], 15, v3
	v_cmp_eq_u32_e64 s[88:89], 23, v3
	v_cmp_eq_u32_e64 s[90:91], 24, v3
	v_writelane_b32 v255, s0, 1
	v_cmp_eq_u32_e64 s[92:93], 25, v3
	v_cmp_eq_u32_e64 s[94:95], 26, v3
	v_writelane_b32 v255, s1, 2
	v_cmp_eq_u32_e64 s[0:1], 16, v3
	v_cmp_eq_u32_e64 s[96:97], 27, v3
	v_cmp_eq_u32_e64 s[6:7], 28, v3
	v_writelane_b32 v255, s0, 3
	v_cmp_eq_u32_e64 s[8:9], 29, v3
	v_cmp_eq_u32_e64 s[10:11], 30, v3
	v_writelane_b32 v255, s1, 4
	v_cmp_eq_u32_e64 s[0:1], 17, v3
	v_cmp_eq_u32_e64 s[12:13], 31, v3
	v_cmp_eq_u32_e64 s[14:15], 32, v3
	v_writelane_b32 v255, s0, 5
	v_cmp_eq_u32_e64 s[16:17], 33, v3
	v_cmp_eq_u32_e64 s[18:19], 34, v3
	v_writelane_b32 v255, s1, 6
	v_cmp_eq_u32_e64 s[0:1], 18, v3
	v_cmp_eq_u32_e64 s[20:21], 35, v3
	v_cmp_eq_u32_e64 s[22:23], 36, v3
	v_writelane_b32 v255, s0, 7
	v_cmp_eq_u32_e64 s[24:25], 37, v3
	v_cmp_eq_u32_e64 s[26:27], 38, v3
	v_writelane_b32 v255, s1, 8
	v_cmp_eq_u32_e64 s[0:1], 19, v3
	v_cmp_eq_u32_e64 s[28:29], 39, v3
	v_cmp_eq_u32_e64 s[30:31], 40, v3
	v_writelane_b32 v255, s0, 9
	v_cmp_eq_u32_e64 s[34:35], 41, v3
	v_cmp_eq_u32_e64 s[36:37], 42, v3
	v_writelane_b32 v255, s1, 10
	v_cmp_eq_u32_e64 s[0:1], 20, v3
	v_cmp_eq_u32_e64 s[38:39], 43, v3
	v_cmp_eq_u32_e64 s[40:41], 44, v3
	v_writelane_b32 v255, s0, 11
	v_cmp_eq_u32_e64 s[76:77], 45, v3
	v_cmp_eq_u32_e64 s[4:5], 46, v3
	v_writelane_b32 v255, s1, 12
	v_cmp_eq_u32_e64 s[0:1], 21, v3
	v_cmp_eq_u32_e64 s[42:43], 47, v3
	v_cmp_eq_u32_e64 s[44:45], 49, v3
	v_writelane_b32 v255, s0, 13
	v_cmp_eq_u32_e64 s[46:47], 50, v3
	v_cmp_eq_u32_e64 s[48:49], 51, v3
	v_writelane_b32 v255, s1, 14
	v_cmp_eq_u32_e64 s[0:1], 22, v3
	v_cmp_eq_u32_e64 s[50:51], 52, v3
	v_cmp_eq_u32_e64 s[52:53], 53, v3
	v_writelane_b32 v255, s0, 15
	v_cmp_eq_u32_e64 s[54:55], 54, v3
	v_cmp_eq_u32_e64 s[56:57], 55, v3
	v_writelane_b32 v255, s1, 16
	v_cmp_eq_u32_e64 s[0:1], 48, v3
	v_cmp_eq_u32_e64 s[58:59], 56, v3
	v_cmp_eq_u32_e64 s[60:61], 57, v3
	v_cmp_eq_u32_e64 s[62:63], 58, v3
	v_cmp_eq_u32_e64 s[64:65], 59, v3
	v_cmp_eq_u32_e64 s[66:67], 60, v3
	v_cmp_eq_u32_e64 s[68:69], 61, v3
	v_cmp_eq_u32_e64 s[70:71], 62, v3
	v_cmp_eq_u32_e64 s[72:73], 63, v3
	s_mov_b64 s[74:75], 0
	v_lshlrev_b32_e32 v0, 1, v2
	v_lshlrev_b32_e32 v86, 1, v4
	s_branch .LBB0_397

.LBB0_708:
	s_or_b64 exec, exec, s[0:1]
	v_readlane_b32 s77, v254, 14
	s_waitcnt lgkmcnt(0)
	s_barrier
	s_setprio 0
